# grid barrier: acquire invalidate issued by wave 1 at barrier entry (concurrent with the leader's arrive/poll), all workgroups poll the global generation word
# speedup vs baseline: 1.0300x; 1.0009x over previous
.LBB0_22:
	s_or_b64 exec, exec, s[0:1]
	s_waitcnt vmcnt(0) lgkmcnt(0)
	s_barrier
	s_mov_b64 s[0:1], 0

.LBB0_577:
	s_waitcnt vmcnt(0)
	s_waitcnt vmcnt(0) lgkmcnt(0)
	s_barrier
	v_readlane_b32 s0, v255, 7
	s_nop 3
	s_cmp_lg_u32 s0, 1
	s_cbranch_scc1 .Lgb_noinv
	buffer_inv sc1
.Lgb_noinv:
	s_and_saveexec_b64 s[0:1], s[4:5]
	s_cbranch_execz .LBB0_22
	v_readlane_b32 s4, v255, 38
	s_waitcnt vmcnt(0) expcnt(0) lgkmcnt(0)
	s_nop 0
	v_mov_b32_e32 v0, s4
	ds_read_b32 v2, v0
	v_readlane_b32 s4, v255, 39
	s_waitcnt lgkmcnt(0)
	v_cmp_ne_u32_e32 vcc, 0, v2
	v_mov_b32_e32 v0, s4
	ds_read_b32 v0, v0
	s_cbranch_vccnz .LBB0_593
	s_load_dwordx2 s[4:5], s[98:99], 0x0
	s_load_dword s6, s[98:99], 0x8
	s_mov_b32 s11, 1
	s_waitcnt lgkmcnt(0)
	s_mul_i32 s10, s5, s4
	s_mul_i32 s10, s10, s6
	s_branch .LBB0_581

.LBB0_595:
	s_or_b64 exec, exec, s[4:5]
	v_cvt_f32_u32_e32 v4, v2
	s_waitcnt vmcnt(0)
	v_readfirstlane_b32 s4, v3
	v_sub_u32_e32 v3, 0, v2
	v_rcp_iflag_f32_e32 v4, v4
	v_add_u32_e32 v5, s4, v1
	v_mul_f32_e32 v4, 0x4f7ffffe, v4
	v_cvt_u32_f32_e32 v4, v4
	v_mul_lo_u32 v1, v3, v4
	v_mul_hi_u32 v1, v4, v1
	v_add_u32_e32 v1, v4, v1
	v_mul_hi_u32 v1, v5, v1
	v_mul_lo_u32 v3, v1, v2
	v_sub_u32_e32 v3, v5, v3
	v_add_u32_e32 v4, 1, v1
	v_cmp_ge_u32_e32 vcc, v3, v2
	s_nop 1
	v_cndmask_b32_e32 v1, v1, v4, vcc
	v_sub_u32_e32 v4, v3, v2
	v_cndmask_b32_e32 v3, v3, v4, vcc
	v_add_u32_e32 v4, 1, v1
	v_cmp_ge_u32_e32 vcc, v3, v2
	v_add_u32_e32 v3, 1, v5
	s_nop 0
	v_cndmask_b32_e32 v1, v1, v4, vcc
	v_mul_lo_u32 v4, v2, v1
	v_add_u32_e32 v2, v4, v2
	v_cmp_ne_u32_e32 vcc, v3, v2
	s_and_saveexec_b64 s[4:5], vcc
	s_xor_b64 s[4:5], exec, s[4:5]
	s_cbranch_execz .LBB0_609
	v_readlane_b32 s6, v254, 42
	v_readlane_b32 s7, v254, 43
	s_waitcnt lgkmcnt(0)
	s_nop 3
	global_load_dword v0, v81, s[6:7] sc1
	s_waitcnt vmcnt(0)
	v_cmp_eq_u32_e32 vcc, v0, v1
	s_and_saveexec_b64 s[6:7], vcc
	s_cbranch_execz .LBB0_608
	s_mov_b64 s[26:27], s[22:23]
	s_mov_b32 s18, 1
	s_mov_b64 s[8:9], 0
	s_branch .LBB0_599
